# G2: the 16 residual loads are issued before the final K step of the tile (their registers are dead there) instead of after its last MFMA
# speedup vs baseline: 1.0111x; 1.0047x over previous
.Ltail_133:
	ds_read_b128 v[98:101], v130
	ds_read_b128 v[102:105], v131 offset:36864
	ds_read_b128 v[106:109], v130 offset:32
	ds_read_b128 v[110:113], v131 offset:36896
	ds_read_b128 v[114:117], v131 offset:41472
	ds_read_b128 v[118:121], v130 offset:4608
	ds_read_b128 v[122:125], v130 offset:4640
	s_waitcnt vmcnt(0)
	ds_read_b128 v[126:129], v131 offset:41504
	s_waitcnt lgkmcnt(3)
	v_mfma_f32_32x32x16_bf16 v[34:49], v[98:101], v[114:117], v[34:49]
	ds_write_b128 v139, v[94:97] offset:18432
	v_mfma_f32_32x32x16_bf16 v[50:65], v[98:101], v[102:105], v[50:65]
	s_waitcnt lgkmcnt(3)
	v_mfma_f32_32x32x16_bf16 v[18:33], v[118:121], v[102:105], v[18:33]
	ds_write_b128 v139, v[90:93] offset:55296
	v_mfma_f32_32x32x16_bf16 v[2:17], v[118:121], v[114:117], v[2:17]
	v_mfma_f32_32x32x16_bf16 v[50:65], v[106:109], v[110:113], v[50:65]
	ds_read_b128 v[90:93], v130 offset:64
	ds_read_b128 v[94:97], v130 offset:4672
	ds_read_b128 v[98:101], v131 offset:36928
	ds_read_b128 v[102:105], v131 offset:41536
	ds_write_b128 v139, v[86:89] offset:23040
	s_waitcnt lgkmcnt(7)
	v_mfma_f32_32x32x16_bf16 v[34:49], v[106:109], v[126:129], v[34:49]
	v_mfma_f32_32x32x16_bf16 v[18:33], v[122:125], v[110:113], v[18:33]
	ds_write_b128 v139, v[82:85] offset:59904
	v_mfma_f32_32x32x16_bf16 v[2:17], v[122:125], v[126:129], v[2:17]
	s_waitcnt lgkmcnt(3)
	v_mfma_f32_32x32x16_bf16 v[50:65], v[90:93], v[98:101], v[50:65]
	ds_read_b128 v[82:85], v130 offset:96
	ds_read_b128 v[86:89], v130 offset:4704
	ds_read_b128 v[106:109], v131 offset:36960
	ds_read_b128 v[110:113], v131 offset:41568
	ds_write_b128 v139, v[78:81] offset:27648
	s_waitcnt lgkmcnt(7)
	v_mfma_f32_32x32x16_bf16 v[34:49], v[90:93], v[102:105], v[34:49]
	v_mfma_f32_32x32x16_bf16 v[18:33], v[94:97], v[98:101], v[18:33]
	ds_write_b128 v139, v[74:77] offset:64512
	v_mfma_f32_32x32x16_bf16 v[2:17], v[94:97], v[102:105], v[2:17]
	s_waitcnt lgkmcnt(3)
	v_mfma_f32_32x32x16_bf16 v[50:65], v[82:85], v[106:109], v[50:65]
	ds_write_b128 v139, v[70:73] offset:32256
	s_waitcnt lgkmcnt(3)
	v_mfma_f32_32x32x16_bf16 v[34:49], v[82:85], v[110:113], v[34:49]
	v_mfma_f32_32x32x16_bf16 v[18:33], v[86:89], v[106:109], v[18:33]
	ds_write_b128 v142, v[66:69] offset:13824
	v_mfma_f32_32x32x16_bf16 v[2:17], v[86:89], v[110:113], v[2:17]
	s_waitcnt lgkmcnt(0)
	s_barrier
	v_lshrrev_b32_e32 v227, 5, v136
	s_lshl_b32 s0, s51, 9
	v_lshl_add_u32 v223, v227, 12, v222
	v_add_u32_e32 v223, s0, v223
	v_mov_b32_e32 v228, v223
	global_load_dwordx4 v[98:101], v228, s[68:69]
	v_add_u32_e32 v228, 0x8000, v228
	global_load_dwordx4 v[102:105], v228, s[68:69]
	v_add_u32_e32 v228, 0x8000, v228
	global_load_dwordx4 v[106:109], v228, s[68:69]
	v_add_u32_e32 v228, 0x8000, v228
	global_load_dwordx4 v[110:113], v228, s[68:69]
	v_add_u32_e32 v228, 0x8000, v228
	global_load_dwordx4 v[114:117], v228, s[68:69]
	v_add_u32_e32 v228, 0x8000, v228
	global_load_dwordx4 v[118:121], v228, s[68:69]
	v_add_u32_e32 v228, 0x8000, v228
	global_load_dwordx4 v[122:125], v228, s[68:69]
	v_add_u32_e32 v228, 0x8000, v228
	global_load_dwordx4 v[126:129], v228, s[68:69]
	v_add_u32_e32 v228, 0x8000, v228
	global_load_dwordx4 v[178:181], v228, s[68:69]
	v_add_u32_e32 v228, 0x8000, v228
	global_load_dwordx4 v[182:185], v228, s[68:69]
	v_add_u32_e32 v228, 0x8000, v228
	global_load_dwordx4 v[186:189], v228, s[68:69]
	v_add_u32_e32 v228, 0x8000, v228
	global_load_dwordx4 v[190:193], v228, s[68:69]
	v_add_u32_e32 v228, 0x8000, v228
	global_load_dwordx4 v[194:197], v228, s[68:69]
	v_add_u32_e32 v228, 0x8000, v228
	global_load_dwordx4 v[198:201], v228, s[68:69]
	v_add_u32_e32 v228, 0x8000, v228
	global_load_dwordx4 v[202:205], v228, s[68:69]
	v_add_u32_e32 v228, 0x8000, v228
	global_load_dwordx4 v[206:209], v228, s[68:69]
	ds_read_b128 v[66:69], v130 offset:18432
	ds_read_b128 v[70:73], v131 offset:55296
	ds_read_b128 v[74:77], v130 offset:18464
	ds_read_b128 v[78:81], v131 offset:55328
	ds_read_b128 v[82:85], v131 offset:59904
	ds_read_b128 v[86:89], v130 offset:23040
	ds_read_b128 v[90:93], v130 offset:23072
	ds_read_b128 v[94:97], v131 offset:59936
	s_waitcnt lgkmcnt(6)
	v_mfma_f32_32x32x16_bf16 v[50:65], v[66:69], v[70:73], v[50:65]
	s_waitcnt lgkmcnt(3)
	v_mfma_f32_32x32x16_bf16 v[34:49], v[66:69], v[82:85], v[34:49]
	s_waitcnt lgkmcnt(2)
	v_mfma_f32_32x32x16_bf16 v[18:33], v[86:89], v[70:73], v[18:33]
	v_mfma_f32_32x32x16_bf16 v[2:17], v[86:89], v[82:85], v[2:17]
	v_mfma_f32_32x32x16_bf16 v[50:65], v[74:77], v[78:81], v[50:65]
	ds_read_b128 v[66:69], v130 offset:18496
	ds_read_b128 v[70:73], v130 offset:23104
	ds_read_b128 v[82:85], v131 offset:55360
	ds_read_b128 v[86:89], v131 offset:59968
	s_waitcnt lgkmcnt(4)
	v_mfma_f32_32x32x16_bf16 v[34:49], v[74:77], v[94:97], v[34:49]
	v_mfma_f32_32x32x16_bf16 v[18:33], v[90:93], v[78:81], v[18:33]
	v_mfma_f32_32x32x16_bf16 v[2:17], v[90:93], v[94:97], v[2:17]
	s_waitcnt lgkmcnt(1)
	v_mfma_f32_32x32x16_bf16 v[50:65], v[66:69], v[82:85], v[50:65]
	ds_read_b128 v[74:77], v130 offset:18528
	ds_read_b128 v[78:81], v130 offset:23136
	ds_read_b128 v[90:93], v131 offset:55392
	ds_read_b128 v[94:97], v131 offset:60000
	s_waitcnt lgkmcnt(4)
	v_mfma_f32_32x32x16_bf16 v[34:49], v[66:69], v[86:89], v[34:49]
	v_mfma_f32_32x32x16_bf16 v[18:33], v[70:73], v[82:85], v[18:33]
	v_mfma_f32_32x32x16_bf16 v[2:17], v[70:73], v[86:89], v[2:17]
	s_waitcnt lgkmcnt(1)
	v_mfma_f32_32x32x16_bf16 v[50:65], v[74:77], v[90:93], v[50:65]
	s_waitcnt lgkmcnt(0)
	v_mfma_f32_32x32x16_bf16 v[34:49], v[74:77], v[94:97], v[34:49]
	v_mfma_f32_32x32x16_bf16 v[18:33], v[78:81], v[90:93], v[18:33]
	v_mfma_f32_32x32x16_bf16 v[2:17], v[78:81], v[94:97], v[2:17]
	v_lshl_or_b32 v66, v138, 2, v141
	s_movk_i32 s0, 0x210
	v_and_or_b32 v67, v136, 64, v137
	v_mul_lo_u32 v66, v66, s0
	v_lshl_add_u32 v66, v67, 2, v66
	s_barrier
	s_nop 3
	ds_write2_b32 v66, v50, v34 offset1:32
	ds_write2_b32 v66, v51, v35 offset0:132 offset1:164
	v_add_u32_e32 v34, 0x400, v66
	ds_write2_b32 v34, v52, v36 offset0:8 offset1:40
	ds_write2_b32 v34, v53, v37 offset0:140 offset1:172
	v_add_u32_e32 v34, 0x1000, v66
	ds_write2_b32 v34, v54, v38 offset0:32 offset1:64
	ds_write2_b32 v34, v55, v39 offset0:164 offset1:196
	v_add_u32_e32 v34, 0x1400, v66
	ds_write2_b32 v34, v56, v40 offset0:40 offset1:72
	ds_write2_b32 v34, v57, v41 offset0:172 offset1:204
	v_add_u32_e32 v34, 0x2000, v66
	ds_write2_b32 v34, v58, v42 offset0:64 offset1:96
	ds_write2_b32 v34, v59, v43 offset0:196 offset1:228
	v_add_u32_e32 v34, 0x2400, v66
	ds_write2_b32 v34, v60, v44 offset0:72 offset1:104
	ds_write2_b32 v34, v61, v45 offset0:204 offset1:236
	v_add_u32_e32 v34, 0x3000, v66
	ds_write2_b32 v34, v62, v46 offset0:96 offset1:128
	v_add_u32_e32 v34, 0x3200, v66
	ds_write2_b32 v34, v63, v47 offset0:100 offset1:132
	v_add_u32_e32 v34, 0x3400, v66
	ds_write2_b32 v34, v64, v48 offset0:104 offset1:136
	v_add_u32_e32 v34, 0x3600, v66
	ds_write2_b32 v34, v65, v49 offset0:108 offset1:140
	v_add_u32_e32 v34, 0x4000, v66
	ds_write2_b32 v34, v18, v2 offset0:128 offset1:160
	v_add_u32_e32 v2, 0x4400, v66
	ds_write2_b32 v2, v19, v3 offset0:4 offset1:36
	ds_write2_b32 v2, v20, v4 offset0:136 offset1:168
	v_add_u32_e32 v2, 0x4800, v66
	ds_write2_b32 v2, v21, v5 offset0:12 offset1:44
	v_add_u32_e32 v2, 0x5000, v66
	ds_write2_b32 v2, v22, v6 offset0:160 offset1:192
	v_add_u32_e32 v2, 0x5400, v66
	ds_write2_b32 v2, v23, v7 offset0:36 offset1:68
	ds_write2_b32 v2, v24, v8 offset0:168 offset1:200
	v_add_u32_e32 v2, 0x5800, v66
	ds_write2_b32 v2, v25, v9 offset0:44 offset1:76
	v_add_u32_e32 v2, 0x6000, v66
	ds_write2_b32 v2, v26, v10 offset0:192 offset1:224
	v_add_u32_e32 v2, 0x6400, v66
	ds_write2_b32 v2, v27, v11 offset0:68 offset1:100
	ds_write2_b32 v2, v28, v12 offset0:200 offset1:232
	v_add_u32_e32 v2, 0x6800, v66
	ds_write2_b32 v2, v29, v13 offset0:76 offset1:108
	v_add_u32_e32 v2, 0x7200, v66
	ds_write2_b32 v2, v30, v14 offset0:96 offset1:128
	v_add_u32_e32 v2, 0x7400, v66
	ds_write2_b32 v2, v31, v15 offset0:100 offset1:132
	v_add_u32_e32 v2, 0x7600, v66
	ds_write2_b32 v2, v32, v16 offset0:104 offset1:136
	v_add_u32_e32 v2, 0x7800, v66
	ds_write2_b32 v2, v33, v17 offset0:108 offset1:140
	s_waitcnt lgkmcnt(0)
	s_barrier
	v_lshrrev_b32_e32 v227, 5, v136
	v_mul_u32_u24_e32 v225, 0x210, v227
	v_add_u32_e32 v225, v225, v222
	ds_read_b128 v[2:5], v225
	ds_read_b128 v[6:9], v225 offset:4224
	ds_read_b128 v[10:13], v225 offset:8448
	ds_read_b128 v[14:17], v225 offset:12672
	ds_read_b128 v[18:21], v225 offset:16896
	ds_read_b128 v[22:25], v225 offset:21120
	ds_read_b128 v[26:29], v225 offset:25344
	ds_read_b128 v[30:33], v225 offset:29568
	ds_read_b128 v[34:37], v225 offset:33792
	ds_read_b128 v[38:41], v225 offset:38016
	ds_read_b128 v[42:45], v225 offset:42240
	ds_read_b128 v[46:49], v225 offset:46464
	ds_read_b128 v[50:53], v225 offset:50688
	ds_read_b128 v[54:57], v225 offset:54912
	ds_read_b128 v[58:61], v225 offset:59136
	ds_read_b128 v[62:65], v225 offset:63360
	v_mul_u32_u24_e32 v224, 0x880, v227
	s_lshl_b32 s0, s51, 8
	v_lshrrev_b32_e32 v228, 1, v222
	v_add3_u32 v224, v224, v228, s0
	v_lshlrev_b32_e32 v226, 2, v227
	s_waitcnt lgkmcnt(0)
	s_waitcnt vmcnt(15)
	v_pk_fma_f32 v[2:3], v[2:3], v[210:211], v[98:99]
	v_pk_fma_f32 v[4:5], v[4:5], v[212:213], v[100:101]
	s_waitcnt vmcnt(14)
	v_pk_fma_f32 v[6:7], v[6:7], v[210:211], v[102:103]
	v_pk_fma_f32 v[8:9], v[8:9], v[212:213], v[104:105]
	s_waitcnt vmcnt(13)
	v_pk_fma_f32 v[10:11], v[10:11], v[210:211], v[106:107]
	v_pk_fma_f32 v[12:13], v[12:13], v[212:213], v[108:109]
	s_waitcnt vmcnt(12)
	v_pk_fma_f32 v[14:15], v[14:15], v[210:211], v[110:111]
	v_pk_fma_f32 v[16:17], v[16:17], v[212:213], v[112:113]
	s_waitcnt vmcnt(11)
	v_pk_fma_f32 v[18:19], v[18:19], v[210:211], v[114:115]
	v_pk_fma_f32 v[20:21], v[20:21], v[212:213], v[116:117]
	s_waitcnt vmcnt(10)
	v_pk_fma_f32 v[22:23], v[22:23], v[210:211], v[118:119]
	v_pk_fma_f32 v[24:25], v[24:25], v[212:213], v[120:121]
	s_waitcnt vmcnt(9)
	v_pk_fma_f32 v[26:27], v[26:27], v[210:211], v[122:123]
	v_pk_fma_f32 v[28:29], v[28:29], v[212:213], v[124:125]
	s_waitcnt vmcnt(8)
	v_pk_fma_f32 v[30:31], v[30:31], v[210:211], v[126:127]
	v_pk_fma_f32 v[32:33], v[32:33], v[212:213], v[128:129]
	s_waitcnt vmcnt(7)
	v_pk_fma_f32 v[34:35], v[34:35], v[210:211], v[178:179]
	v_pk_fma_f32 v[36:37], v[36:37], v[212:213], v[180:181]
	s_waitcnt vmcnt(6)
	v_pk_fma_f32 v[38:39], v[38:39], v[210:211], v[182:183]
	v_pk_fma_f32 v[40:41], v[40:41], v[212:213], v[184:185]
	s_waitcnt vmcnt(5)
	v_pk_fma_f32 v[42:43], v[42:43], v[210:211], v[186:187]
	v_pk_fma_f32 v[44:45], v[44:45], v[212:213], v[188:189]
	s_waitcnt vmcnt(4)
	v_pk_fma_f32 v[46:47], v[46:47], v[210:211], v[190:191]
	v_pk_fma_f32 v[48:49], v[48:49], v[212:213], v[192:193]
	s_waitcnt vmcnt(3)
	v_pk_fma_f32 v[50:51], v[50:51], v[210:211], v[194:195]
	v_pk_fma_f32 v[52:53], v[52:53], v[212:213], v[196:197]
	s_waitcnt vmcnt(2)
	v_pk_fma_f32 v[54:55], v[54:55], v[210:211], v[198:199]
	v_pk_fma_f32 v[56:57], v[56:57], v[212:213], v[200:201]
	s_waitcnt vmcnt(1)
	v_pk_fma_f32 v[58:59], v[58:59], v[210:211], v[202:203]
	v_pk_fma_f32 v[60:61], v[60:61], v[212:213], v[204:205]
	s_waitcnt vmcnt(0)
	v_pk_fma_f32 v[62:63], v[62:63], v[210:211], v[206:207]
	v_pk_fma_f32 v[64:65], v[64:65], v[212:213], v[208:209]
	v_mov_b32_e32 v228, v223
	global_store_dwordx4 v228, v[2:5], s[70:71] sc0 sc1
	v_add_u32_e32 v228, 0x8000, v228
	global_store_dwordx4 v228, v[6:9], s[70:71] sc0 sc1
	v_add_u32_e32 v228, 0x8000, v228
	global_store_dwordx4 v228, v[10:13], s[70:71] sc0 sc1
	v_add_u32_e32 v228, 0x8000, v228
	global_store_dwordx4 v228, v[14:17], s[70:71] sc0 sc1
	v_add_u32_e32 v228, 0x8000, v228
	global_store_dwordx4 v228, v[18:21], s[70:71] sc0 sc1
	v_add_u32_e32 v228, 0x8000, v228
	global_store_dwordx4 v228, v[22:25], s[70:71] sc0 sc1
	v_add_u32_e32 v228, 0x8000, v228
	global_store_dwordx4 v228, v[26:29], s[70:71] sc0 sc1
	v_add_u32_e32 v228, 0x8000, v228
	global_store_dwordx4 v228, v[30:33], s[70:71] sc0 sc1
	v_add_u32_e32 v228, 0x8000, v228
	global_store_dwordx4 v228, v[34:37], s[70:71] sc0 sc1
	v_add_u32_e32 v228, 0x8000, v228
	global_store_dwordx4 v228, v[38:41], s[70:71] sc0 sc1
	v_add_u32_e32 v228, 0x8000, v228
	global_store_dwordx4 v228, v[42:45], s[70:71] sc0 sc1
	v_add_u32_e32 v228, 0x8000, v228
	global_store_dwordx4 v228, v[46:49], s[70:71] sc0 sc1
	v_add_u32_e32 v228, 0x8000, v228
	global_store_dwordx4 v228, v[50:53], s[70:71] sc0 sc1
	v_add_u32_e32 v228, 0x8000, v228
	global_store_dwordx4 v228, v[54:57], s[70:71] sc0 sc1
	v_add_u32_e32 v228, 0x8000, v228
	global_store_dwordx4 v228, v[58:61], s[70:71] sc0 sc1
	v_add_u32_e32 v228, 0x8000, v228
	global_store_dwordx4 v228, v[62:65], s[70:71] sc0 sc1
	s_cmp_lg_u64 s[54:55], 0
	s_cbranch_scc0 .LBB0_122
	v_pk_add_f32 v[218:219], v[218:219], 1.0 op_sel_hi:[1,0]
	v_pk_add_f32 v[220:221], v[220:221], 1.0 op_sel_hi:[1,0]
	v_pk_mul_f32 v[214:215], v[214:215], v[218:219]
	v_pk_mul_f32 v[216:217], v[216:217], v[220:221]
	v_pk_mul_f32 v[98:99], v[2:3], v[2:3]
	v_pk_mul_f32 v[100:101], v[4:5], v[4:5]
	v_pk_mul_f32 v[102:103], v[6:7], v[6:7]
	v_pk_mul_f32 v[104:105], v[8:9], v[8:9]
	v_pk_mul_f32 v[106:107], v[10:11], v[10:11]
	v_pk_mul_f32 v[108:109], v[12:13], v[12:13]
	v_pk_mul_f32 v[110:111], v[14:15], v[14:15]
	v_pk_mul_f32 v[112:113], v[16:17], v[16:17]
	v_pk_mul_f32 v[114:115], v[18:19], v[18:19]
	v_pk_mul_f32 v[116:117], v[20:21], v[20:21]
	v_pk_mul_f32 v[118:119], v[22:23], v[22:23]
	v_pk_mul_f32 v[120:121], v[24:25], v[24:25]
	v_pk_mul_f32 v[122:123], v[26:27], v[26:27]
	v_pk_mul_f32 v[124:125], v[28:29], v[28:29]
	v_pk_mul_f32 v[126:127], v[30:31], v[30:31]
	v_pk_mul_f32 v[128:129], v[32:33], v[32:33]
	v_pk_mul_f32 v[178:179], v[34:35], v[34:35]
	v_pk_mul_f32 v[180:181], v[36:37], v[36:37]
	v_pk_mul_f32 v[182:183], v[38:39], v[38:39]
	v_pk_mul_f32 v[184:185], v[40:41], v[40:41]
	v_pk_mul_f32 v[186:187], v[42:43], v[42:43]
	v_pk_mul_f32 v[188:189], v[44:45], v[44:45]
	v_pk_mul_f32 v[190:191], v[46:47], v[46:47]
	v_pk_mul_f32 v[192:193], v[48:49], v[48:49]
	v_pk_mul_f32 v[194:195], v[50:51], v[50:51]
	v_pk_mul_f32 v[196:197], v[52:53], v[52:53]
	v_pk_mul_f32 v[198:199], v[54:55], v[54:55]
	v_pk_mul_f32 v[200:201], v[56:57], v[56:57]
	v_pk_mul_f32 v[202:203], v[58:59], v[58:59]
	v_pk_mul_f32 v[204:205], v[60:61], v[60:61]
	v_pk_mul_f32 v[206:207], v[62:63], v[62:63]
	v_pk_mul_f32 v[208:209], v[64:65], v[64:65]
	v_add_f32_e32 v229, v98, v99
	v_add_f32_e32 v230, v102, v103
	v_add_f32_e32 v231, v106, v107
	v_add_f32_e32 v232, v110, v111
	v_add_f32_e32 v233, v114, v115
	v_add_f32_e32 v234, v118, v119
	v_add_f32_e32 v235, v122, v123
	v_add_f32_e32 v236, v126, v127
	v_add_f32_e32 v237, v178, v179
	v_add_f32_e32 v238, v182, v183
	v_add_f32_e32 v239, v186, v187
	v_add_f32_e32 v240, v190, v191
	v_add_f32_e32 v241, v194, v195
	v_add_f32_e32 v242, v198, v199
	v_add_f32_e32 v243, v202, v203
	v_add_f32_e32 v244, v206, v207
	v_add_f32_e32 v229, v229, v100
	v_add_f32_e32 v230, v230, v104
	v_add_f32_e32 v231, v231, v108
	v_add_f32_e32 v232, v232, v112
	v_add_f32_e32 v233, v233, v116
	v_add_f32_e32 v234, v234, v120
	v_add_f32_e32 v235, v235, v124
	v_add_f32_e32 v236, v236, v128
	v_add_f32_e32 v237, v237, v180
	v_add_f32_e32 v238, v238, v184
	v_add_f32_e32 v239, v239, v188
	v_add_f32_e32 v240, v240, v192
	v_add_f32_e32 v241, v241, v196
	v_add_f32_e32 v242, v242, v200
	v_add_f32_e32 v243, v243, v204
	v_add_f32_e32 v244, v244, v208
	v_add_f32_e32 v229, v229, v101
	v_add_f32_e32 v230, v230, v105
	v_add_f32_e32 v231, v231, v109
	v_add_f32_e32 v232, v232, v113
	v_add_f32_e32 v233, v233, v117
	v_add_f32_e32 v234, v234, v121
	v_add_f32_e32 v235, v235, v125
	v_add_f32_e32 v236, v236, v129
	v_add_f32_e32 v237, v237, v181
	v_add_f32_e32 v238, v238, v185
	v_add_f32_e32 v239, v239, v189
	v_add_f32_e32 v240, v240, v193
	v_add_f32_e32 v241, v241, v197
	v_add_f32_e32 v242, v242, v201
	v_add_f32_e32 v243, v243, v205
	v_add_f32_e32 v244, v244, v209
	v_pk_mul_f32 v[2:3], v[2:3], v[214:215]
	v_pk_mul_f32 v[4:5], v[4:5], v[216:217]
	v_pk_mul_f32 v[6:7], v[6:7], v[214:215]
	v_pk_mul_f32 v[8:9], v[8:9], v[216:217]
	v_pk_mul_f32 v[10:11], v[10:11], v[214:215]
	v_pk_mul_f32 v[12:13], v[12:13], v[216:217]
	v_pk_mul_f32 v[14:15], v[14:15], v[214:215]
	v_pk_mul_f32 v[16:17], v[16:17], v[216:217]
	v_pk_mul_f32 v[18:19], v[18:19], v[214:215]
	v_pk_mul_f32 v[20:21], v[20:21], v[216:217]
	v_pk_mul_f32 v[22:23], v[22:23], v[214:215]
	v_pk_mul_f32 v[24:25], v[24:25], v[216:217]
	v_pk_mul_f32 v[26:27], v[26:27], v[214:215]
	v_pk_mul_f32 v[28:29], v[28:29], v[216:217]
	v_pk_mul_f32 v[30:31], v[30:31], v[214:215]
	v_pk_mul_f32 v[32:33], v[32:33], v[216:217]
	v_pk_mul_f32 v[34:35], v[34:35], v[214:215]
	v_pk_mul_f32 v[36:37], v[36:37], v[216:217]
	v_pk_mul_f32 v[38:39], v[38:39], v[214:215]
	v_pk_mul_f32 v[40:41], v[40:41], v[216:217]
	v_pk_mul_f32 v[42:43], v[42:43], v[214:215]
	v_pk_mul_f32 v[44:45], v[44:45], v[216:217]
	v_pk_mul_f32 v[46:47], v[46:47], v[214:215]
	v_pk_mul_f32 v[48:49], v[48:49], v[216:217]
	v_pk_mul_f32 v[50:51], v[50:51], v[214:215]
	v_pk_mul_f32 v[52:53], v[52:53], v[216:217]
	v_pk_mul_f32 v[54:55], v[54:55], v[214:215]
	v_pk_mul_f32 v[56:57], v[56:57], v[216:217]
	v_pk_mul_f32 v[58:59], v[58:59], v[214:215]
	v_pk_mul_f32 v[60:61], v[60:61], v[216:217]
	v_pk_mul_f32 v[62:63], v[62:63], v[214:215]
	v_pk_mul_f32 v[64:65], v[64:65], v[216:217]
	v_cvt_pk_bf16_f32 v98, v2, v3
	v_cvt_pk_bf16_f32 v99, v4, v5
	v_cvt_pk_bf16_f32 v102, v6, v7
	v_cvt_pk_bf16_f32 v103, v8, v9
	v_cvt_pk_bf16_f32 v106, v10, v11
	v_cvt_pk_bf16_f32 v107, v12, v13
	v_cvt_pk_bf16_f32 v110, v14, v15
	v_cvt_pk_bf16_f32 v111, v16, v17
	v_cvt_pk_bf16_f32 v114, v18, v19
	v_cvt_pk_bf16_f32 v115, v20, v21
	v_cvt_pk_bf16_f32 v118, v22, v23
	v_cvt_pk_bf16_f32 v119, v24, v25
	v_cvt_pk_bf16_f32 v122, v26, v27
	v_cvt_pk_bf16_f32 v123, v28, v29
	v_cvt_pk_bf16_f32 v126, v30, v31
	v_cvt_pk_bf16_f32 v127, v32, v33
	v_cvt_pk_bf16_f32 v178, v34, v35
	v_cvt_pk_bf16_f32 v179, v36, v37
	v_cvt_pk_bf16_f32 v182, v38, v39
	v_cvt_pk_bf16_f32 v183, v40, v41
	v_cvt_pk_bf16_f32 v186, v42, v43
	v_cvt_pk_bf16_f32 v187, v44, v45
	v_cvt_pk_bf16_f32 v190, v46, v47
	v_cvt_pk_bf16_f32 v191, v48, v49
	v_cvt_pk_bf16_f32 v194, v50, v51
	v_cvt_pk_bf16_f32 v195, v52, v53
	v_cvt_pk_bf16_f32 v198, v54, v55
	v_cvt_pk_bf16_f32 v199, v56, v57
	v_cvt_pk_bf16_f32 v202, v58, v59
	v_cvt_pk_bf16_f32 v203, v60, v61
	v_cvt_pk_bf16_f32 v206, v62, v63
	v_cvt_pk_bf16_f32 v207, v64, v65
	v_readlane_b32 s56, v248, 13
	v_readlane_b32 s57, v248, 14
	s_mul_i32 s0, s51, 0xa000
	s_lshl_b32 s1, s2, 2
	s_add_i32 s0, s0, s1
	s_add_u32 s56, s56, s0
	s_addc_u32 s57, s57, 0
	s_mul_i32 s0, s2, 0x880
	s_add_u32 s58, s8, s0
	s_addc_u32 s59, s9, 0
	v_mov_b32_e32 v228, v224
	global_store_dwordx2 v228, v[98:99], s[58:59] sc0 sc1
	v_add_u32_e32 v228, 0x4400, v228
	global_store_dwordx2 v228, v[102:103], s[58:59] sc0 sc1
	v_add_u32_e32 v228, 0x4400, v228
	global_store_dwordx2 v228, v[106:107], s[58:59] sc0 sc1
	v_add_u32_e32 v228, 0x4400, v228
	global_store_dwordx2 v228, v[110:111], s[58:59] sc0 sc1
	v_add_u32_e32 v228, 0x4400, v228
	global_store_dwordx2 v228, v[114:115], s[58:59] sc0 sc1
	v_add_u32_e32 v228, 0x4400, v228
	global_store_dwordx2 v228, v[118:119], s[58:59] sc0 sc1
	v_add_u32_e32 v228, 0x4400, v228
	global_store_dwordx2 v228, v[122:123], s[58:59] sc0 sc1
	v_add_u32_e32 v228, 0x4400, v228
	global_store_dwordx2 v228, v[126:127], s[58:59] sc0 sc1
	v_add_u32_e32 v228, 0x4400, v228
	global_store_dwordx2 v228, v[178:179], s[58:59] sc0 sc1
	v_add_u32_e32 v228, 0x4400, v228
	global_store_dwordx2 v228, v[182:183], s[58:59] sc0 sc1
	v_add_u32_e32 v228, 0x4400, v228
	global_store_dwordx2 v228, v[186:187], s[58:59] sc0 sc1
	v_add_u32_e32 v228, 0x4400, v228
	global_store_dwordx2 v228, v[190:191], s[58:59] sc0 sc1
	v_add_u32_e32 v228, 0x4400, v228
	global_store_dwordx2 v228, v[194:195], s[58:59] sc0 sc1
	v_add_u32_e32 v228, 0x4400, v228
	global_store_dwordx2 v228, v[198:199], s[58:59] sc0 sc1
	v_add_u32_e32 v228, 0x4400, v228
	global_store_dwordx2 v228, v[202:203], s[58:59] sc0 sc1
	v_add_u32_e32 v228, 0x4400, v228
	global_store_dwordx2 v228, v[206:207], s[58:59] sc0 sc1
	v_add_f32_dpp v229, v229, v229 quad_perm:[1,0,3,2] row_mask:0xf bank_mask:0xf
	v_add_f32_dpp v230, v230, v230 quad_perm:[1,0,3,2] row_mask:0xf bank_mask:0xf
	v_add_f32_dpp v231, v231, v231 quad_perm:[1,0,3,2] row_mask:0xf bank_mask:0xf
	v_add_f32_dpp v232, v232, v232 quad_perm:[1,0,3,2] row_mask:0xf bank_mask:0xf
	v_add_f32_dpp v233, v233, v233 quad_perm:[1,0,3,2] row_mask:0xf bank_mask:0xf
	v_add_f32_dpp v234, v234, v234 quad_perm:[1,0,3,2] row_mask:0xf bank_mask:0xf
	v_add_f32_dpp v235, v235, v235 quad_perm:[1,0,3,2] row_mask:0xf bank_mask:0xf
	v_add_f32_dpp v236, v236, v236 quad_perm:[1,0,3,2] row_mask:0xf bank_mask:0xf
	v_add_f32_dpp v237, v237, v237 quad_perm:[1,0,3,2] row_mask:0xf bank_mask:0xf
	v_add_f32_dpp v238, v238, v238 quad_perm:[1,0,3,2] row_mask:0xf bank_mask:0xf
	v_add_f32_dpp v239, v239, v239 quad_perm:[1,0,3,2] row_mask:0xf bank_mask:0xf
	v_add_f32_dpp v240, v240, v240 quad_perm:[1,0,3,2] row_mask:0xf bank_mask:0xf
	v_add_f32_dpp v241, v241, v241 quad_perm:[1,0,3,2] row_mask:0xf bank_mask:0xf
	v_add_f32_dpp v242, v242, v242 quad_perm:[1,0,3,2] row_mask:0xf bank_mask:0xf
	v_add_f32_dpp v243, v243, v243 quad_perm:[1,0,3,2] row_mask:0xf bank_mask:0xf
	v_add_f32_dpp v244, v244, v244 quad_perm:[1,0,3,2] row_mask:0xf bank_mask:0xf
	v_add_f32_dpp v229, v229, v229 quad_perm:[2,3,0,1] row_mask:0xf bank_mask:0xf
	v_add_f32_dpp v230, v230, v230 quad_perm:[2,3,0,1] row_mask:0xf bank_mask:0xf
	v_add_f32_dpp v231, v231, v231 quad_perm:[2,3,0,1] row_mask:0xf bank_mask:0xf
	v_add_f32_dpp v232, v232, v232 quad_perm:[2,3,0,1] row_mask:0xf bank_mask:0xf
	v_add_f32_dpp v233, v233, v233 quad_perm:[2,3,0,1] row_mask:0xf bank_mask:0xf
	v_add_f32_dpp v234, v234, v234 quad_perm:[2,3,0,1] row_mask:0xf bank_mask:0xf
	v_add_f32_dpp v235, v235, v235 quad_perm:[2,3,0,1] row_mask:0xf bank_mask:0xf
	v_add_f32_dpp v236, v236, v236 quad_perm:[2,3,0,1] row_mask:0xf bank_mask:0xf
	v_add_f32_dpp v237, v237, v237 quad_perm:[2,3,0,1] row_mask:0xf bank_mask:0xf
	v_add_f32_dpp v238, v238, v238 quad_perm:[2,3,0,1] row_mask:0xf bank_mask:0xf
	v_add_f32_dpp v239, v239, v239 quad_perm:[2,3,0,1] row_mask:0xf bank_mask:0xf
	v_add_f32_dpp v240, v240, v240 quad_perm:[2,3,0,1] row_mask:0xf bank_mask:0xf
	v_add_f32_dpp v241, v241, v241 quad_perm:[2,3,0,1] row_mask:0xf bank_mask:0xf
	v_add_f32_dpp v242, v242, v242 quad_perm:[2,3,0,1] row_mask:0xf bank_mask:0xf
	v_add_f32_dpp v243, v243, v243 quad_perm:[2,3,0,1] row_mask:0xf bank_mask:0xf
	v_add_f32_dpp v244, v244, v244 quad_perm:[2,3,0,1] row_mask:0xf bank_mask:0xf
	v_add_f32_dpp v229, v229, v229 row_ror:4 row_mask:0xf bank_mask:0xf
	v_add_f32_dpp v230, v230, v230 row_ror:4 row_mask:0xf bank_mask:0xf
	v_add_f32_dpp v231, v231, v231 row_ror:4 row_mask:0xf bank_mask:0xf
	v_add_f32_dpp v232, v232, v232 row_ror:4 row_mask:0xf bank_mask:0xf
	v_add_f32_dpp v233, v233, v233 row_ror:4 row_mask:0xf bank_mask:0xf
	v_add_f32_dpp v234, v234, v234 row_ror:4 row_mask:0xf bank_mask:0xf
	v_add_f32_dpp v235, v235, v235 row_ror:4 row_mask:0xf bank_mask:0xf
	v_add_f32_dpp v236, v236, v236 row_ror:4 row_mask:0xf bank_mask:0xf
	v_add_f32_dpp v237, v237, v237 row_ror:4 row_mask:0xf bank_mask:0xf
	v_add_f32_dpp v238, v238, v238 row_ror:4 row_mask:0xf bank_mask:0xf
	v_add_f32_dpp v239, v239, v239 row_ror:4 row_mask:0xf bank_mask:0xf
	v_add_f32_dpp v240, v240, v240 row_ror:4 row_mask:0xf bank_mask:0xf
	v_add_f32_dpp v241, v241, v241 row_ror:4 row_mask:0xf bank_mask:0xf
	v_add_f32_dpp v242, v242, v242 row_ror:4 row_mask:0xf bank_mask:0xf
	v_add_f32_dpp v243, v243, v243 row_ror:4 row_mask:0xf bank_mask:0xf
	v_add_f32_dpp v244, v244, v244 row_ror:4 row_mask:0xf bank_mask:0xf
	v_add_f32_dpp v229, v229, v229 row_ror:8 row_mask:0xf bank_mask:0xf
	v_add_f32_dpp v230, v230, v230 row_ror:8 row_mask:0xf bank_mask:0xf
	v_add_f32_dpp v231, v231, v231 row_ror:8 row_mask:0xf bank_mask:0xf
	v_add_f32_dpp v232, v232, v232 row_ror:8 row_mask:0xf bank_mask:0xf
	v_add_f32_dpp v233, v233, v233 row_ror:8 row_mask:0xf bank_mask:0xf
	v_add_f32_dpp v234, v234, v234 row_ror:8 row_mask:0xf bank_mask:0xf
	v_add_f32_dpp v235, v235, v235 row_ror:8 row_mask:0xf bank_mask:0xf
	v_add_f32_dpp v236, v236, v236 row_ror:8 row_mask:0xf bank_mask:0xf
	v_add_f32_dpp v237, v237, v237 row_ror:8 row_mask:0xf bank_mask:0xf
	v_add_f32_dpp v238, v238, v238 row_ror:8 row_mask:0xf bank_mask:0xf
	v_add_f32_dpp v239, v239, v239 row_ror:8 row_mask:0xf bank_mask:0xf
	v_add_f32_dpp v240, v240, v240 row_ror:8 row_mask:0xf bank_mask:0xf
	v_add_f32_dpp v241, v241, v241 row_ror:8 row_mask:0xf bank_mask:0xf
	v_add_f32_dpp v242, v242, v242 row_ror:8 row_mask:0xf bank_mask:0xf
	v_add_f32_dpp v243, v243, v243 row_ror:8 row_mask:0xf bank_mask:0xf
	v_add_f32_dpp v244, v244, v244 row_ror:8 row_mask:0xf bank_mask:0xf
	v_add_f32_dpp v229, v229, v229 row_bcast:15 row_mask:0xa bank_mask:0xf
	v_add_f32_dpp v230, v230, v230 row_bcast:15 row_mask:0xa bank_mask:0xf
	v_add_f32_dpp v231, v231, v231 row_bcast:15 row_mask:0xa bank_mask:0xf
	v_add_f32_dpp v232, v232, v232 row_bcast:15 row_mask:0xa bank_mask:0xf
	v_add_f32_dpp v233, v233, v233 row_bcast:15 row_mask:0xa bank_mask:0xf
	v_add_f32_dpp v234, v234, v234 row_bcast:15 row_mask:0xa bank_mask:0xf
	v_add_f32_dpp v235, v235, v235 row_bcast:15 row_mask:0xa bank_mask:0xf
	v_add_f32_dpp v236, v236, v236 row_bcast:15 row_mask:0xa bank_mask:0xf
	v_add_f32_dpp v237, v237, v237 row_bcast:15 row_mask:0xa bank_mask:0xf
	v_add_f32_dpp v238, v238, v238 row_bcast:15 row_mask:0xa bank_mask:0xf
	v_add_f32_dpp v239, v239, v239 row_bcast:15 row_mask:0xa bank_mask:0xf
	v_add_f32_dpp v240, v240, v240 row_bcast:15 row_mask:0xa bank_mask:0xf
	v_add_f32_dpp v241, v241, v241 row_bcast:15 row_mask:0xa bank_mask:0xf
	v_add_f32_dpp v242, v242, v242 row_bcast:15 row_mask:0xa bank_mask:0xf
	v_add_f32_dpp v243, v243, v243 row_bcast:15 row_mask:0xa bank_mask:0xf
	v_add_f32_dpp v244, v244, v244 row_bcast:15 row_mask:0xa bank_mask:0xf
	s_mov_b64 s[40:41], exec
	s_mov_b32 s0, 0x80000000
	s_mov_b32 s1, 0x80000000
	s_mov_b64 exec, s[0:1]
	global_store_dword v226, v229, s[56:57]
	global_store_dword v226, v230, s[56:57] offset:32
	global_store_dword v226, v231, s[56:57] offset:64
	global_store_dword v226, v232, s[56:57] offset:96
	global_store_dword v226, v233, s[56:57] offset:128
	global_store_dword v226, v234, s[56:57] offset:160
	global_store_dword v226, v235, s[56:57] offset:192
	global_store_dword v226, v236, s[56:57] offset:224
	global_store_dword v226, v237, s[56:57] offset:256
	global_store_dword v226, v238, s[56:57] offset:288
	global_store_dword v226, v239, s[56:57] offset:320
	global_store_dword v226, v240, s[56:57] offset:352
	global_store_dword v226, v241, s[56:57] offset:384
	global_store_dword v226, v242, s[56:57] offset:416
	global_store_dword v226, v243, s[56:57] offset:448
	global_store_dword v226, v244, s[56:57] offset:480
	s_mov_b64 exec, s[40:41]
	s_branch .LBB0_122
